# P7 unit boundary: store addresses from one base + immediate offsets; next-tile index by shift/mask when the tile group is full
# baseline (speedup 1.0000x reference)
.LBB0_953:
	s_add_i32 s41, s41, 1
	s_mul_i32 s2, s41, s47
	s_mul_hi_u32 s3, s41, s48
	s_add_i32 s3, s3, s2
	s_mul_i32 s2, s41, s48
	s_add_u32 s14, s2, s33
	s_addc_u32 s15, s3, s31
	v_cmp_gt_i64_e32 vcc, s[14:15], v[144:145]
	v_cmp_lt_i64_e64 s[2:3], s[14:15], v[142:143]
	s_cbranch_vccnz .LBB0_955
	s_ashr_i32 s10, s14, 31
	s_lshr_b32 s10, s10, 29
	s_add_i32 s10, s14, s10
	s_ashr_i32 s11, s10, 3
	s_and_b32 s10, s10, -8
	s_sub_i32 s10, s14, s10
	s_cmp_lt_i32 s10, 0
	s_cselect_b32 s12, s34, 0x370
	s_mul_i32 s10, s10, s12
	s_add_i32 s10, s10, s11
	s_mul_hi_i32 s11, s10, 0x2e8ba2e9
	s_lshr_b32 s12, s11, 31
	s_ashr_i32 s11, s11, 4
	s_add_i32 s11, s11, s12
	s_lshl_b32 s12, s11, 2
	s_sub_i32 s13, 0x140, s12
	s_min_i32 s13, s13, 4
	s_mulk_i32 s11, 0x58
	s_sub_i32 s11, s10, s11
	s_cmp_eq_u32 s13, 4
	s_cbranch_scc0 .Lp7hdr_slow
	s_lshr_b32 s10, s11, 2
	s_and_b32 s11, s11, 3
	s_add_i32 s12, s12, s11
	s_branch .LBB0_955
.Lp7hdr_slow:
	s_abs_i32 s14, s13
	v_cvt_f32_u32_e32 v0, s14
	s_sub_i32 s16, 0, s14
	v_rcp_iflag_f32_e32 v0, v0
	s_abs_i32 s10, s11
	s_xor_b32 s15, s11, s13
	s_ashr_i32 s15, s15, 31
	v_mul_f32_e32 v0, 0x4f7ffffe, v0
	v_cvt_u32_f32_e32 v0, v0
	s_nop 0
	v_readfirstlane_b32 s17, v0
	s_mul_i32 s16, s16, s17
	s_mul_hi_u32 s16, s17, s16
	s_add_i32 s17, s17, s16
	s_mul_hi_u32 s16, s10, s17
	s_mul_i32 s17, s16, s14
	s_sub_i32 s10, s10, s17
	s_add_i32 s24, s16, 1
	s_sub_i32 s17, s10, s14
	s_cmp_ge_u32 s10, s14
	s_cselect_b32 s16, s24, s16
	s_cselect_b32 s10, s17, s10
	s_add_i32 s17, s16, 1
	s_cmp_ge_u32 s10, s14
	s_cselect_b32 s10, s17, s16
	s_xor_b32 s10, s10, s15
	s_sub_i32 s10, s10, s15
	s_mul_i32 s13, s10, s13
	s_sub_i32 s11, s11, s13
	s_add_i32 s12, s12, s11

.LBB0_959:
	v_mul_f32_e32 v153, 0xbfb8aa3b, v124
	v_exp_f32_e32 v153, v153
	v_mul_f32_e32 v154, 0xbfb8aa3b, v125
	v_exp_f32_e32 v156, v154
	v_lshl_add_u32 v146, s18, 8, v148
	v_ashrrev_i32_e32 v147, 31, v146
	v_lshlrev_b64 v[154:155], 6, v[146:147]
	v_add_f32_e32 v147, 1.0, v153
	v_rcp_f32_e32 v147, v147
	v_add_f32_e32 v153, 1.0, v156
	v_rcp_f32_e32 v153, v153
	s_lshl_b32 s11, s19, 2
	v_mul_f32_e32 v124, v124, v147
	v_mul_f32_e32 v124, v124, v116
	v_mul_f32_e32 v116, v125, v153
	v_mul_f32_e32 v125, 0xbfb8aa3b, v126
	v_exp_f32_e32 v125, v125
	v_mul_f32_e32 v147, 0xbfb8aa3b, v127
	v_exp_f32_e32 v147, v147
	v_mul_f32_e32 v153, v116, v117
	v_add_f32_e32 v116, 1.0, v125
	v_rcp_f32_e32 v116, v116
	v_add_f32_e32 v117, 1.0, v147
	v_mul_f32_e32 v125, 0xbfb8aa3b, v120
	v_rcp_f32_e32 v117, v117
	v_exp_f32_e32 v125, v125
	v_mul_f32_e32 v116, v126, v116
	v_mul_f32_e32 v118, v116, v118
	v_mul_f32_e32 v116, v127, v117
	v_add_f32_e32 v117, 1.0, v125
	v_rcp_f32_e32 v117, v117
	v_mul_f32_e32 v125, 0xbfb8aa3b, v121
	v_mul_f32_e32 v119, v116, v119
	v_exp_f32_e32 v125, v125
	v_mul_f32_e32 v116, v120, v117
	v_mul_f32_e32 v120, v116, v112
	v_mul_f32_e32 v116, 0xbfb8aa3b, v122
	v_exp_f32_e32 v116, v116
	v_mul_f32_e32 v117, 0xbfb8aa3b, v123
	v_exp_f32_e32 v117, v117
	v_add_f32_e32 v112, 1.0, v125
	v_rcp_f32_e32 v112, v112
	v_add_f32_e32 v116, 1.0, v116
	v_rcp_f32_e32 v116, v116
	v_add_f32_e32 v117, 1.0, v117
	s_or_b32 s11, s11, s44
	v_rcp_f32_e32 v117, v117
	s_mul_hi_i32 s13, s11, 0x500000
	s_mul_i32 s11, s11, 0x500000
	s_add_u32 s18, s42, s11
	v_mul_f32_e32 v112, v121, v112
	s_addc_u32 s19, s43, s13
	v_mul_f32_e32 v121, v112, v113
	v_mul_f32_e32 v112, v122, v116
	v_lshl_add_u64 v[154:155], s[18:19], 0, v[154:155]
	v_mul_f32_e32 v122, v112, v114
	v_mul_f32_e32 v112, v123, v117
	v_mul_f32_e32 v115, v112, v115
	v_lshl_add_u64 v[116:117], v[154:155], 0, v[136:137]
	v_cvt_pk_bf16_f32 v112, v124, v153
	v_cvt_pk_bf16_f32 v113, v118, v119
	v_cvt_pk_bf16_f32 v114, v120, v121
	v_cvt_pk_bf16_f32 v115, v122, v115
	v_mov_b32_e32 v254, v116
	v_mov_b32_e32 v255, v117
	global_store_dwordx4 v[116:117], v[112:115], off
	s_andn2_b64 vcc, exec, s[2:3]
	s_mov_b64 s[2:3], -1
	v_mul_f32_e32 v114, 0xbfb8aa3b, v108
	v_exp_f32_e32 v114, v114
	v_mul_f32_e32 v115, 0xbfb8aa3b, v109
	v_exp_f32_e32 v115, v115
	v_add_f32_e32 v114, 1.0, v114
	v_rcp_f32_e32 v114, v114
	v_add_f32_e32 v115, 1.0, v115
	v_rcp_f32_e32 v115, v115
	v_mul_f32_e32 v108, v108, v114
	v_mul_f32_e32 v108, v108, v100
	v_mul_f32_e32 v100, v109, v115
	v_mul_f32_e32 v109, 0xbfb8aa3b, v110
	v_exp_f32_e32 v109, v109
	v_mul_f32_e32 v114, 0xbfb8aa3b, v111
	v_exp_f32_e32 v114, v114
	v_mul_f32_e32 v115, v100, v101
	v_add_f32_e32 v100, 1.0, v109
	v_rcp_f32_e32 v100, v100
	v_add_f32_e32 v101, 1.0, v114
	v_mul_f32_e32 v109, 0xbfb8aa3b, v104
	v_rcp_f32_e32 v101, v101
	v_exp_f32_e32 v109, v109
	v_mul_f32_e32 v100, v110, v100
	v_mul_f32_e32 v102, v100, v102
	v_mul_f32_e32 v100, v111, v101
	v_add_f32_e32 v101, 1.0, v109
	v_rcp_f32_e32 v101, v101
	v_mul_f32_e32 v109, 0xbfb8aa3b, v105
	v_mul_f32_e32 v103, v100, v103
	v_exp_f32_e32 v109, v109
	v_mul_f32_e32 v100, v104, v101
	v_mul_f32_e32 v104, v100, v96
	v_mul_f32_e32 v100, 0xbfb8aa3b, v106
	v_exp_f32_e32 v100, v100
	v_mul_f32_e32 v101, 0xbfb8aa3b, v107
	v_exp_f32_e32 v101, v101
	v_add_f32_e32 v96, 1.0, v109
	v_rcp_f32_e32 v96, v96
	v_add_f32_e32 v100, 1.0, v100
	v_rcp_f32_e32 v100, v100
	v_add_f32_e32 v101, 1.0, v101
	v_rcp_f32_e32 v101, v101
	v_mul_f32_e32 v96, v105, v96
	v_mul_f32_e32 v105, v96, v97
	v_mul_f32_e32 v96, v106, v100
	v_mul_f32_e32 v106, v96, v98
	v_mul_f32_e32 v96, v107, v101
	v_mul_f32_e32 v99, v96, v99
	v_cvt_pk_bf16_f32 v96, v108, v115
	v_cvt_pk_bf16_f32 v97, v102, v103
	v_cvt_pk_bf16_f32 v98, v104, v105
	v_cvt_pk_bf16_f32 v99, v106, v99
	global_store_dwordx4 v[254:255], v[96:99], off offset:1024
	s_nop 1
	v_mul_f32_e32 v98, 0xbfb8aa3b, v92
	v_exp_f32_e32 v98, v98
	v_mul_f32_e32 v99, 0xbfb8aa3b, v93
	v_exp_f32_e32 v99, v99
	v_add_f32_e32 v98, 1.0, v98
	v_rcp_f32_e32 v98, v98
	v_add_f32_e32 v99, 1.0, v99
	v_rcp_f32_e32 v99, v99
	v_mul_f32_e32 v92, v92, v98
	v_mul_f32_e32 v92, v92, v84
	v_mul_f32_e32 v84, v93, v99
	v_mul_f32_e32 v93, 0xbfb8aa3b, v94
	v_exp_f32_e32 v93, v93
	v_mul_f32_e32 v98, 0xbfb8aa3b, v95
	v_exp_f32_e32 v98, v98
	v_mul_f32_e32 v99, v84, v85
	v_add_f32_e32 v84, 1.0, v93
	v_rcp_f32_e32 v84, v84
	v_add_f32_e32 v85, 1.0, v98
	v_mul_f32_e32 v93, 0xbfb8aa3b, v88
	v_rcp_f32_e32 v85, v85
	v_exp_f32_e32 v93, v93
	v_mul_f32_e32 v84, v94, v84
	v_mul_f32_e32 v86, v84, v86
	v_mul_f32_e32 v84, v95, v85
	v_add_f32_e32 v85, 1.0, v93
	v_rcp_f32_e32 v85, v85
	v_mul_f32_e32 v93, 0xbfb8aa3b, v89
	v_mul_f32_e32 v87, v84, v87
	v_exp_f32_e32 v93, v93
	v_mul_f32_e32 v84, v88, v85
	v_mul_f32_e32 v88, v84, v80
	v_mul_f32_e32 v84, 0xbfb8aa3b, v90
	v_exp_f32_e32 v84, v84
	v_mul_f32_e32 v85, 0xbfb8aa3b, v91
	v_exp_f32_e32 v85, v85
	v_add_f32_e32 v80, 1.0, v93
	v_rcp_f32_e32 v80, v80
	v_add_f32_e32 v84, 1.0, v84
	v_rcp_f32_e32 v84, v84
	v_add_f32_e32 v85, 1.0, v85
	v_rcp_f32_e32 v85, v85
	v_mul_f32_e32 v80, v89, v80
	v_mul_f32_e32 v89, v80, v81
	v_mul_f32_e32 v80, v90, v84
	v_mul_f32_e32 v90, v80, v82
	v_mul_f32_e32 v80, v91, v85
	v_mul_f32_e32 v83, v80, v83
	v_cvt_pk_bf16_f32 v80, v92, v99
	v_cvt_pk_bf16_f32 v81, v86, v87
	v_cvt_pk_bf16_f32 v82, v88, v89
	v_cvt_pk_bf16_f32 v83, v90, v83
	global_store_dwordx4 v[254:255], v[80:83], off offset:2048
	s_nop 1
	v_mul_f32_e32 v82, 0xbfb8aa3b, v76
	v_exp_f32_e32 v82, v82
	v_mul_f32_e32 v83, 0xbfb8aa3b, v77
	v_exp_f32_e32 v83, v83
	v_add_f32_e32 v82, 1.0, v82
	v_rcp_f32_e32 v82, v82
	v_add_f32_e32 v83, 1.0, v83
	v_rcp_f32_e32 v83, v83
	v_mul_f32_e32 v76, v76, v82
	v_mul_f32_e32 v76, v76, v68
	v_mul_f32_e32 v68, v77, v83
	v_mul_f32_e32 v77, 0xbfb8aa3b, v78
	v_exp_f32_e32 v77, v77
	v_mul_f32_e32 v82, 0xbfb8aa3b, v79
	v_exp_f32_e32 v82, v82
	v_mul_f32_e32 v83, v68, v69
	v_add_f32_e32 v68, 1.0, v77
	v_rcp_f32_e32 v68, v68
	v_add_f32_e32 v69, 1.0, v82
	v_mul_f32_e32 v77, 0xbfb8aa3b, v72
	v_rcp_f32_e32 v69, v69
	v_exp_f32_e32 v77, v77
	v_mul_f32_e32 v68, v78, v68
	v_mul_f32_e32 v70, v68, v70
	v_mul_f32_e32 v68, v79, v69
	v_add_f32_e32 v69, 1.0, v77
	v_rcp_f32_e32 v69, v69
	v_mul_f32_e32 v77, 0xbfb8aa3b, v73
	v_mul_f32_e32 v71, v68, v71
	v_exp_f32_e32 v77, v77
	v_mul_f32_e32 v68, v72, v69
	v_mul_f32_e32 v72, v68, v64
	v_mul_f32_e32 v68, 0xbfb8aa3b, v74
	v_exp_f32_e32 v68, v68
	v_mul_f32_e32 v69, 0xbfb8aa3b, v75
	v_exp_f32_e32 v69, v69
	v_add_f32_e32 v64, 1.0, v77
	v_rcp_f32_e32 v64, v64
	v_add_f32_e32 v68, 1.0, v68
	v_rcp_f32_e32 v68, v68
	v_add_f32_e32 v69, 1.0, v69
	v_rcp_f32_e32 v69, v69
	v_mul_f32_e32 v64, v73, v64
	v_mul_f32_e32 v73, v64, v65
	v_mul_f32_e32 v64, v74, v68
	v_mul_f32_e32 v74, v64, v66
	v_mul_f32_e32 v64, v75, v69
	v_mul_f32_e32 v67, v64, v67
	v_cvt_pk_bf16_f32 v64, v76, v83
	v_cvt_pk_bf16_f32 v65, v70, v71
	v_cvt_pk_bf16_f32 v66, v72, v73
	v_cvt_pk_bf16_f32 v67, v74, v67
	global_store_dwordx4 v[254:255], v[64:67], off offset:3072
	s_nop 1
	v_mul_f32_e32 v66, 0xbfb8aa3b, v60
	v_exp_f32_e32 v66, v66
	v_mul_f32_e32 v67, 0xbfb8aa3b, v61
	v_exp_f32_e32 v67, v67
	v_add_f32_e32 v66, 1.0, v66
	v_rcp_f32_e32 v66, v66
	v_add_f32_e32 v67, 1.0, v67
	v_rcp_f32_e32 v67, v67
	v_mul_f32_e32 v60, v60, v66
	v_mul_f32_e32 v60, v60, v52
	v_mul_f32_e32 v52, v61, v67
	v_mul_f32_e32 v61, 0xbfb8aa3b, v62
	v_exp_f32_e32 v61, v61
	v_mul_f32_e32 v66, 0xbfb8aa3b, v63
	v_exp_f32_e32 v66, v66
	v_mul_f32_e32 v67, v52, v53
	v_add_f32_e32 v52, 1.0, v61
	v_rcp_f32_e32 v52, v52
	v_add_f32_e32 v53, 1.0, v66
	v_mul_f32_e32 v61, 0xbfb8aa3b, v56
	v_rcp_f32_e32 v53, v53
	v_exp_f32_e32 v61, v61
	v_mul_f32_e32 v52, v62, v52
	v_mul_f32_e32 v54, v52, v54
	v_mul_f32_e32 v52, v63, v53
	v_add_f32_e32 v53, 1.0, v61
	v_rcp_f32_e32 v53, v53
	v_mul_f32_e32 v61, 0xbfb8aa3b, v57
	v_mul_f32_e32 v55, v52, v55
	v_exp_f32_e32 v61, v61
	v_mul_f32_e32 v52, v56, v53
	v_mul_f32_e32 v56, v52, v48
	v_mul_f32_e32 v52, 0xbfb8aa3b, v58
	v_exp_f32_e32 v52, v52
	v_mul_f32_e32 v53, 0xbfb8aa3b, v59
	v_exp_f32_e32 v53, v53
	v_add_f32_e32 v48, 1.0, v61
	v_rcp_f32_e32 v48, v48
	v_add_f32_e32 v52, 1.0, v52
	v_rcp_f32_e32 v52, v52
	v_add_f32_e32 v53, 1.0, v53
	v_rcp_f32_e32 v53, v53
	v_mul_f32_e32 v48, v57, v48
	v_mul_f32_e32 v57, v48, v49
	v_mul_f32_e32 v48, v58, v52
	v_mul_f32_e32 v58, v48, v50
	v_mul_f32_e32 v48, v59, v53
	v_mul_f32_e32 v51, v48, v51
	v_cvt_pk_bf16_f32 v48, v60, v67
	v_cvt_pk_bf16_f32 v49, v54, v55
	v_cvt_pk_bf16_f32 v50, v56, v57
	v_cvt_pk_bf16_f32 v51, v58, v51
	s_mov_b64 s[98:99], 0x2000
	v_lshl_add_u64 v[254:255], v[254:255], 0, s[98:99]
	global_store_dwordx4 v[254:255], v[48:51], off
	s_nop 1
	v_mul_f32_e32 v50, 0xbfb8aa3b, v44
	v_exp_f32_e32 v50, v50
	v_mul_f32_e32 v51, 0xbfb8aa3b, v45
	v_exp_f32_e32 v51, v51
	v_add_f32_e32 v50, 1.0, v50
	v_rcp_f32_e32 v50, v50
	v_add_f32_e32 v51, 1.0, v51
	v_rcp_f32_e32 v51, v51
	v_mul_f32_e32 v44, v44, v50
	v_mul_f32_e32 v44, v44, v36
	v_mul_f32_e32 v36, v45, v51
	v_mul_f32_e32 v45, 0xbfb8aa3b, v46
	v_exp_f32_e32 v45, v45
	v_mul_f32_e32 v50, 0xbfb8aa3b, v47
	v_exp_f32_e32 v50, v50
	v_mul_f32_e32 v51, v36, v37
	v_add_f32_e32 v36, 1.0, v45
	v_rcp_f32_e32 v36, v36
	v_add_f32_e32 v37, 1.0, v50
	v_mul_f32_e32 v45, 0xbfb8aa3b, v40
	v_rcp_f32_e32 v37, v37
	v_exp_f32_e32 v45, v45
	v_mul_f32_e32 v36, v46, v36
	v_mul_f32_e32 v38, v36, v38
	v_mul_f32_e32 v36, v47, v37
	v_add_f32_e32 v37, 1.0, v45
	v_rcp_f32_e32 v37, v37
	v_mul_f32_e32 v45, 0xbfb8aa3b, v41
	v_mul_f32_e32 v39, v36, v39
	v_exp_f32_e32 v45, v45
	v_mul_f32_e32 v36, v40, v37
	v_mul_f32_e32 v40, v36, v32
	v_mul_f32_e32 v36, 0xbfb8aa3b, v42
	v_exp_f32_e32 v36, v36
	v_mul_f32_e32 v37, 0xbfb8aa3b, v43
	v_exp_f32_e32 v37, v37
	v_add_f32_e32 v32, 1.0, v45
	v_rcp_f32_e32 v32, v32
	v_add_f32_e32 v36, 1.0, v36
	v_rcp_f32_e32 v36, v36
	v_add_f32_e32 v37, 1.0, v37
	v_rcp_f32_e32 v37, v37
	v_mul_f32_e32 v32, v41, v32
	v_mul_f32_e32 v41, v32, v33
	v_mul_f32_e32 v32, v42, v36
	v_mul_f32_e32 v42, v32, v34
	v_mul_f32_e32 v32, v43, v37
	v_mul_f32_e32 v35, v32, v35
	v_cvt_pk_bf16_f32 v32, v44, v51
	v_cvt_pk_bf16_f32 v33, v38, v39
	v_cvt_pk_bf16_f32 v34, v40, v41
	v_cvt_pk_bf16_f32 v35, v42, v35
	global_store_dwordx4 v[254:255], v[32:35], off offset:1024
	s_nop 1
	v_mul_f32_e32 v34, 0xbfb8aa3b, v28
	v_exp_f32_e32 v34, v34
	v_mul_f32_e32 v35, 0xbfb8aa3b, v29
	v_exp_f32_e32 v35, v35
	v_add_f32_e32 v34, 1.0, v34
	v_rcp_f32_e32 v34, v34
	v_add_f32_e32 v35, 1.0, v35
	v_rcp_f32_e32 v35, v35
	v_mul_f32_e32 v28, v28, v34
	v_mul_f32_e32 v28, v28, v20
	v_mul_f32_e32 v20, v29, v35
	v_mul_f32_e32 v29, 0xbfb8aa3b, v30
	v_exp_f32_e32 v29, v29
	v_mul_f32_e32 v34, 0xbfb8aa3b, v31
	v_exp_f32_e32 v34, v34
	v_mul_f32_e32 v35, v20, v21
	v_add_f32_e32 v20, 1.0, v29
	v_rcp_f32_e32 v20, v20
	v_add_f32_e32 v21, 1.0, v34
	v_mul_f32_e32 v29, 0xbfb8aa3b, v24
	v_rcp_f32_e32 v21, v21
	v_exp_f32_e32 v29, v29
	v_mul_f32_e32 v20, v30, v20
	v_mul_f32_e32 v22, v20, v22
	v_mul_f32_e32 v20, v31, v21
	v_add_f32_e32 v21, 1.0, v29
	v_rcp_f32_e32 v21, v21
	v_mul_f32_e32 v29, 0xbfb8aa3b, v25
	v_mul_f32_e32 v23, v20, v23
	v_exp_f32_e32 v29, v29
	v_mul_f32_e32 v20, v24, v21
	v_mul_f32_e32 v24, v20, v16
	v_mul_f32_e32 v20, 0xbfb8aa3b, v26
	v_exp_f32_e32 v20, v20
	v_mul_f32_e32 v21, 0xbfb8aa3b, v27
	v_exp_f32_e32 v21, v21
	v_add_f32_e32 v16, 1.0, v29
	v_rcp_f32_e32 v16, v16
	v_add_f32_e32 v20, 1.0, v20
	v_rcp_f32_e32 v20, v20
	v_add_f32_e32 v21, 1.0, v21
	v_rcp_f32_e32 v21, v21
	v_mul_f32_e32 v16, v25, v16
	v_mul_f32_e32 v25, v16, v17
	v_mul_f32_e32 v16, v26, v20
	v_mul_f32_e32 v26, v16, v18
	v_mul_f32_e32 v16, v27, v21
	v_mul_f32_e32 v19, v16, v19
	v_cvt_pk_bf16_f32 v16, v28, v35
	v_cvt_pk_bf16_f32 v17, v22, v23
	v_cvt_pk_bf16_f32 v18, v24, v25
	v_cvt_pk_bf16_f32 v19, v26, v19
	global_store_dwordx4 v[254:255], v[16:19], off offset:2048
	s_nop 1
	v_mul_f32_e32 v18, 0xbfb8aa3b, v12
	v_exp_f32_e32 v18, v18
	v_mul_f32_e32 v19, 0xbfb8aa3b, v13
	v_exp_f32_e32 v19, v19
	v_add_f32_e32 v18, 1.0, v18
	v_rcp_f32_e32 v18, v18
	v_add_f32_e32 v19, 1.0, v19
	v_rcp_f32_e32 v19, v19
	v_mul_f32_e32 v12, v12, v18
	v_mul_f32_e32 v12, v12, v4
	v_mul_f32_e32 v4, v13, v19
	v_mul_f32_e32 v13, 0xbfb8aa3b, v14
	v_exp_f32_e32 v13, v13
	v_mul_f32_e32 v18, 0xbfb8aa3b, v15
	v_exp_f32_e32 v18, v18
	v_mul_f32_e32 v19, v4, v5
	v_add_f32_e32 v4, 1.0, v13
	v_rcp_f32_e32 v4, v4
	v_add_f32_e32 v5, 1.0, v18
	v_mul_f32_e32 v13, 0xbfb8aa3b, v8
	v_rcp_f32_e32 v5, v5
	v_exp_f32_e32 v13, v13
	v_mul_f32_e32 v4, v14, v4
	v_mul_f32_e32 v6, v4, v6
	v_mul_f32_e32 v4, v15, v5
	v_add_f32_e32 v5, 1.0, v13
	v_rcp_f32_e32 v5, v5
	v_mul_f32_e32 v13, 0xbfb8aa3b, v9
	v_mul_f32_e32 v7, v4, v7
	v_exp_f32_e32 v13, v13
	v_mul_f32_e32 v4, v8, v5
	v_mul_f32_e32 v8, v4, v0
	v_mul_f32_e32 v4, 0xbfb8aa3b, v10
	v_exp_f32_e32 v4, v4
	v_mul_f32_e32 v5, 0xbfb8aa3b, v11
	v_exp_f32_e32 v5, v5
	v_add_f32_e32 v0, 1.0, v13
	v_rcp_f32_e32 v0, v0
	v_add_f32_e32 v4, 1.0, v4
	v_rcp_f32_e32 v4, v4
	v_add_f32_e32 v5, 1.0, v5
	v_rcp_f32_e32 v5, v5
	v_mul_f32_e32 v0, v9, v0
	v_mul_f32_e32 v9, v0, v1
	v_mul_f32_e32 v0, v10, v4
	v_mul_f32_e32 v10, v0, v2
	v_mul_f32_e32 v0, v11, v5
	v_mul_f32_e32 v3, v0, v3
	v_cvt_pk_bf16_f32 v0, v12, v19
	v_cvt_pk_bf16_f32 v1, v6, v7
	v_cvt_pk_bf16_f32 v2, v8, v9
	v_cvt_pk_bf16_f32 v3, v10, v3
	global_store_dwordx4 v[254:255], v[0:3], off offset:3072
	s_cbranch_vccnz .LBB0_952
	s_andn2_b64 vcc, exec, s[4:5]
	s_cbranch_vccnz .LBB0_951
	s_barrier
	s_branch .LBB0_951

	.amdhsa_kernel _Z8fwd_mega4Args
		.amdhsa_group_segment_fixed_size 0
		.amdhsa_private_segment_fixed_size 0
		.amdhsa_kernarg_size 432
		.amdhsa_user_sgpr_count 2
		.amdhsa_user_sgpr_dispatch_ptr 0
		.amdhsa_user_sgpr_queue_ptr 0
		.amdhsa_user_sgpr_kernarg_segment_ptr 1
		.amdhsa_user_sgpr_dispatch_id 0
		.amdhsa_user_sgpr_kernarg_preload_length 0
		.amdhsa_user_sgpr_kernarg_preload_offset 0
		.amdhsa_user_sgpr_private_segment_size 0
		.amdhsa_uses_dynamic_stack 0
		.amdhsa_enable_private_segment 0
		.amdhsa_system_sgpr_workgroup_id_x 1
		.amdhsa_system_sgpr_workgroup_id_y 0
		.amdhsa_system_sgpr_workgroup_id_z 0
		.amdhsa_system_sgpr_workgroup_info 0
		.amdhsa_system_vgpr_workitem_id 2
		.amdhsa_next_free_vgpr 256
		.amdhsa_next_free_sgpr 100
		.amdhsa_accum_offset 256
		.amdhsa_reserve_vcc 1
		.amdhsa_float_round_mode_32 0
		.amdhsa_float_round_mode_16_64 0
		.amdhsa_float_denorm_mode_32 3
		.amdhsa_float_denorm_mode_16_64 3
		.amdhsa_dx10_clamp 1
		.amdhsa_ieee_mode 1
		.amdhsa_fp16_overflow 0
		.amdhsa_tg_split 0
		.amdhsa_exception_fp_ieee_invalid_op 0
		.amdhsa_exception_fp_denorm_src 0
		.amdhsa_exception_fp_ieee_div_zero 0
		.amdhsa_exception_fp_ieee_overflow 0
		.amdhsa_exception_fp_ieee_underflow 0
		.amdhsa_exception_fp_ieee_inexact 0
		.amdhsa_exception_int_div_zero 0
	.end_amdhsa_kernel

amdhsa.kernels:
  - .agpr_count:     0
    .args:
      - .offset:         0
        .size:           176
        .value_kind:     by_value
      - .offset:         176
        .size:           4
        .value_kind:     hidden_block_count_x
      - .offset:         180
        .size:           4
        .value_kind:     hidden_block_count_y
      - .offset:         184
        .size:           4
        .value_kind:     hidden_block_count_z
      - .offset:         188
        .size:           2
        .value_kind:     hidden_group_size_x
      - .offset:         190
        .size:           2
        .value_kind:     hidden_group_size_y
      - .offset:         192
        .size:           2
        .value_kind:     hidden_group_size_z
      - .offset:         194
        .size:           2
        .value_kind:     hidden_remainder_x
      - .offset:         196
        .size:           2
        .value_kind:     hidden_remainder_y
      - .offset:         198
        .size:           2
        .value_kind:     hidden_remainder_z
      - .offset:         216
        .size:           8
        .value_kind:     hidden_global_offset_x
      - .offset:         224
        .size:           8
        .value_kind:     hidden_global_offset_y
      - .offset:         232
        .size:           8
        .value_kind:     hidden_global_offset_z
      - .offset:         240
        .size:           2
        .value_kind:     hidden_grid_dims
      - .offset:         264
        .size:           8
        .value_kind:     hidden_multigrid_sync_arg
      - .offset:         296
        .size:           4
        .value_kind:     hidden_dynamic_lds_size
    .group_segment_fixed_size: 0
    .kernarg_segment_align: 8
    .kernarg_segment_size: 432
    .language:       OpenCL C
    .language_version:
      - 2
      - 0
    .max_flat_workgroup_size: 512
    .name:           _Z8fwd_mega4Args
    .private_segment_fixed_size: 0
    .sgpr_count:     106
    .sgpr_spill_count: 3
    .symbol:         _Z8fwd_mega4Args.kd
    .uniform_work_group_size: 1
    .uses_dynamic_stack: false
    .vgpr_count:     256
    .vgpr_spill_count: 0
    .wavefront_size: 64
